# U2: rs prefetch at tile start (as U) plus dead address arithmetic removed from the EpiGU epilogue head
# baseline (speedup 1.0000x reference)
; __device__ __forceinline__ unsigned cvt_pk_bf16(float lo, float hi) { unsigned r; asm volatile("v_cvt_pk_bf16_f32 %0, %1, %2" : "=v"(r) : "v"(lo), "v"(hi)); return r; }
; __device__ __forceinline__ float sigmoidf_(float x) { return __builtin_amdgcn_rcpf(1.0f + __expf(-x)); }
;     __device__ __forceinline__ void operator()(const f32x4 (&acc)[2][2][4][2], const Unit& u, int wr, int wc, int fr, int fq) const {
;         const int row0 = u.pm * 256 + wr * 64 + fr, col0 = u.pn * 128 + wc * 32 + fq * 8;
;         float sv[2][4];
; #pragma unroll
;         for (int ai = 0; ai < 2; ++ai)
; #pragma unroll
;             for (int m = 0; m < 4; ++m) sv[ai][m] = rs[row0 + ai * 128 + m * 16];
; #pragma unroll
;         for (int ai = 0; ai < 2; ++ai)
; #pragma unroll
;             for (int m = 0; m < 4; ++m) {
;                 const int row = row0 + ai * 128 + m * 16; const float s = sv[ai][m];
;                 float o[8];
; #pragma unroll
;                 for (int n = 0; n < 2; ++n)
; #pragma unroll
;                     for (int j = 0; j < 4; ++j) { const float g = acc[ai][0][m][n][j] * s, up = acc[ai][1][m][n][j] * s; o[n * 4 + j] = g * sigmoidf_(g) * up; }
;                 u32x4 w; w.x = cvt_pk_bf16(o[0], o[1]); w.y = cvt_pk_bf16(o[2], o[3]); w.z = cvt_pk_bf16(o[4], o[5]); w.w = cvt_pk_bf16(o[6], o[7]);
;                 *(u32x4*)(ACT + (size_t)row * FF + col0) = w;
.LBB0_728:
	v_lshl_add_u32 v166, s16, 8, v147
	v_readlane_b32 s18, v251, 10
	v_readlane_b32 s19, v251, 11
	v_or_b32_e32 v162, 16, v166
	v_mov_b32_e32 v139, v124
	v_mov_b32_e32 v124, v121
	v_mov_b32_e32 v138, v120
	v_or_b32_e32 v158, 32, v166
	v_or_b32_e32 v154, 48, v166
	v_lshl_or_b32 v168, s17, 7, v151
	v_readlane_b32 s16, v251, 14
	v_readlane_b32 s17, v251, 15
	v_ashrrev_i32_e32 v169, 31, v168
	s_movk_i32 s3, 0x2b00
	v_add_u32_e32 v161, 0x80, v166
	v_add_u32_e32 v157, 0xa0, v166
	v_add_u32_e32 v159, 0x90, v166
	v_add_u32_e32 v155, 0xb0, v166
	s_andn2_b64 vcc, exec, s[6:7]
	v_pk_mul_f32 v[124:125], v[124:125], v[142:143] op_sel_hi:[1,0]
	s_nop 0
	v_mul_f32_e32 v121, 0xbfb8aa3b, v125
	v_exp_f32_e32 v121, v121
	v_pk_mul_f32 v[138:139], v[138:139], v[142:143] op_sel_hi:[1,0]
	v_add_f32_e32 v121, 1.0, v121
	v_rcp_f32_e32 v121, v121
	v_mul_f32_e32 v120, 0xbfb8aa3b, v139
	v_exp_f32_e32 v120, v120
	v_mul_f32_e32 v121, v125, v121
	v_mul_f32_e32 v121, v124, v121
	v_mov_b32_e32 v124, v122
	v_mov_b32_e32 v125, v126
	v_pk_mul_f32 v[124:125], v[124:125], v[142:143] op_sel_hi:[1,0]
	v_mov_b32_e32 v126, v123
	v_mul_f32_e32 v122, 0xbfb8aa3b, v125
	v_exp_f32_e32 v122, v122
	v_add_f32_e32 v120, 1.0, v120
	v_rcp_f32_e32 v120, v120
	v_add_f32_e32 v122, 1.0, v122
	v_rcp_f32_e32 v122, v122
	v_mul_f32_e32 v120, v139, v120
	v_mul_f32_e32 v120, v138, v120
	v_mul_f32_e32 v122, v125, v122
	v_mul_f32_e32 v124, v124, v122
	v_pk_mul_f32 v[122:123], v[126:127], v[142:143] op_sel_hi:[1,0]
	s_nop 0
	v_mul_f32_e32 v125, 0xbfb8aa3b, v123
	v_exp_f32_e32 v125, v125
	s_nop 0
	v_add_f32_e32 v125, 1.0, v125
	v_rcp_f32_e32 v125, v125
	s_nop 0
	v_mul_f32_e32 v123, v123, v125
	v_mul_f32_e32 v125, v122, v123
	v_mov_b32_e32 v122, v116
	v_mov_b32_e32 v123, v112
	v_pk_mul_f32 v[122:123], v[122:123], v[142:143] op_sel_hi:[1,0]
	s_nop 0
	v_mul_f32_e32 v112, 0xbfb8aa3b, v123
	v_exp_f32_e32 v112, v112
	s_nop 0
	v_add_f32_e32 v112, 1.0, v112
	v_rcp_f32_e32 v112, v112
	s_nop 0
	v_mul_f32_e32 v112, v123, v112
	v_mul_f32_e32 v122, v122, v112
	v_mov_b32_e32 v112, v117
	v_pk_mul_f32 v[112:113], v[112:113], v[142:143] op_sel_hi:[1,0]
	s_nop 0
	v_mul_f32_e32 v116, 0xbfb8aa3b, v113
	v_exp_f32_e32 v116, v116
	s_nop 0
	v_add_f32_e32 v116, 1.0, v116
	v_rcp_f32_e32 v116, v116
	s_nop 0
	v_mul_f32_e32 v113, v113, v116
	v_mul_f32_e32 v123, v112, v113
	v_mov_b32_e32 v112, v118
	v_mov_b32_e32 v113, v114
	v_pk_mul_f32 v[112:113], v[112:113], v[142:143] op_sel_hi:[1,0]
	v_cvt_pk_bf16_f32 v116, v120, v121
	v_cvt_pk_bf16_f32 v117, v124, v125
	v_cvt_pk_bf16_f32 v118, v122, v123
	s_nop 0
	v_mul_f32_e32 v114, 0xbfb8aa3b, v113
	v_exp_f32_e32 v114, v114
	s_nop 0
	v_add_f32_e32 v114, 1.0, v114
	v_rcp_f32_e32 v114, v114
	s_nop 0
	v_mul_f32_e32 v113, v113, v114
	v_mov_b32_e32 v114, v119
	v_mul_f32_e32 v126, v112, v113
	v_pk_mul_f32 v[112:113], v[114:115], v[142:143] op_sel_hi:[1,0]
	s_nop 0
	v_mul_f32_e32 v114, 0xbfb8aa3b, v113
	v_exp_f32_e32 v114, v114
	s_nop 0
	v_add_f32_e32 v114, 1.0, v114
	v_rcp_f32_e32 v114, v114
	s_nop 0
	v_mul_f32_e32 v113, v113, v114
	v_mul_f32_e32 v112, v112, v113
	v_cvt_pk_bf16_f32 v119, v126, v112
	v_mov_b64_e32 v[112:113], s[16:17]
	v_mad_i64_i32 v[120:121], s[16:17], v166, s3, v[112:113]
	v_lshlrev_b64 v[114:115], 1, v[168:169]
	v_lshl_add_u64 v[120:121], v[120:121], 0, v[114:115]
	global_store_dwordx4 v[120:121], v[116:119], off
	s_nop 1
	v_mov_b32_e32 v116, v104
	v_mov_b32_e32 v117, v108
	v_pk_mul_f32 v[116:117], v[116:117], v[190:191] op_sel_hi:[1,0]
	v_mov_b32_e32 v108, v105
	v_mul_f32_e32 v104, 0xbfb8aa3b, v117
	v_exp_f32_e32 v104, v104
	s_nop 0
	v_add_f32_e32 v104, 1.0, v104
	v_rcp_f32_e32 v104, v104
	s_nop 0
	v_mul_f32_e32 v104, v117, v104
	v_mul_f32_e32 v116, v116, v104
	v_pk_mul_f32 v[104:105], v[108:109], v[190:191] op_sel_hi:[1,0]
	s_nop 0
	v_mul_f32_e32 v108, 0xbfb8aa3b, v105
	v_exp_f32_e32 v108, v108
	s_nop 0
	v_add_f32_e32 v108, 1.0, v108
	v_rcp_f32_e32 v108, v108
	s_nop 0
	v_mul_f32_e32 v105, v105, v108
	v_mul_f32_e32 v108, v104, v105
	v_mov_b32_e32 v104, v106
	v_mov_b32_e32 v105, v110
	v_pk_mul_f32 v[104:105], v[104:105], v[190:191] op_sel_hi:[1,0]
	v_mov_b32_e32 v110, v107
	v_mul_f32_e32 v106, 0xbfb8aa3b, v105
	v_exp_f32_e32 v106, v106
	s_nop 0
	v_add_f32_e32 v106, 1.0, v106
	v_rcp_f32_e32 v106, v106
	s_nop 0
	v_mul_f32_e32 v105, v105, v106
	v_mul_f32_e32 v106, v104, v105
	v_pk_mul_f32 v[104:105], v[110:111], v[190:191] op_sel_hi:[1,0]
	s_nop 0
	v_mul_f32_e32 v107, 0xbfb8aa3b, v105
	v_exp_f32_e32 v107, v107
	s_nop 0
	v_add_f32_e32 v107, 1.0, v107
	v_rcp_f32_e32 v107, v107
	s_nop 0
	v_mul_f32_e32 v105, v105, v107
	v_mul_f32_e32 v107, v104, v105
	v_mov_b32_e32 v104, v96
	v_mov_b32_e32 v105, v100
	v_pk_mul_f32 v[104:105], v[104:105], v[190:191] op_sel_hi:[1,0]
	v_mov_b32_e32 v100, v97
	v_mul_f32_e32 v96, 0xbfb8aa3b, v105
	v_exp_f32_e32 v96, v96
	s_nop 0
	v_add_f32_e32 v96, 1.0, v96
	v_rcp_f32_e32 v96, v96
	s_nop 0
	v_mul_f32_e32 v96, v105, v96
	v_mul_f32_e32 v104, v104, v96
	v_pk_mul_f32 v[96:97], v[100:101], v[190:191] op_sel_hi:[1,0]
	s_nop 0
	v_mul_f32_e32 v100, 0xbfb8aa3b, v97
	v_exp_f32_e32 v100, v100
	s_nop 0
	v_add_f32_e32 v100, 1.0, v100
	v_rcp_f32_e32 v100, v100
	s_nop 0
	v_mul_f32_e32 v97, v97, v100
	v_mul_f32_e32 v100, v96, v97
	v_mov_b32_e32 v96, v98
	v_mov_b32_e32 v97, v102
	v_pk_mul_f32 v[96:97], v[96:97], v[190:191] op_sel_hi:[1,0]
	v_mov_b32_e32 v102, v99
	v_mul_f32_e32 v98, 0xbfb8aa3b, v97
	v_exp_f32_e32 v98, v98
	s_nop 0
	v_add_f32_e32 v98, 1.0, v98
	v_rcp_f32_e32 v98, v98
	s_nop 0
	v_mul_f32_e32 v97, v97, v98
	v_mul_f32_e32 v101, v96, v97
	v_pk_mul_f32 v[96:97], v[102:103], v[190:191] op_sel_hi:[1,0]
	s_nop 0
	v_mul_f32_e32 v98, 0xbfb8aa3b, v97
; __device__ __forceinline__ unsigned cvt_pk_bf16(float lo, float hi) { unsigned r; asm volatile("v_cvt_pk_bf16_f32 %0, %1, %2" : "=v"(r) : "v"(lo), "v"(hi)); return r; }
; __device__ __forceinline__ float sigmoidf_(float x) { return __builtin_amdgcn_rcpf(1.0f + __expf(-x)); }
;     __device__ __forceinline__ void operator()(const f32x4 (&acc)[2][2][4][2], const Unit& u, int wr, int wc, int fr, int fq) const {
;     ...
;         for (int ai = 0; ai < 2; ++ai)
; #pragma unroll
;             for (int m = 0; m < 4; ++m) {
;                 const int row = row0 + ai * 128 + m * 16; const float s = sv[ai][m];
;                 float o[8];
; #pragma unroll
;                 for (int n = 0; n < 2; ++n)
; #pragma unroll
;                     for (int j = 0; j < 4; ++j) { const float g = acc[ai][0][m][n][j] * s, up = acc[ai][1][m][n][j] * s; o[n * 4 + j] = g * sigmoidf_(g) * up; }
;                 u32x4 w; w.x = cvt_pk_bf16(o[0], o[1]); w.y = cvt_pk_bf16(o[2], o[3]); w.z = cvt_pk_bf16(o[4], o[5]); w.w = cvt_pk_bf16(o[6], o[7]);
;                 *(u32x4*)(ACT + (size_t)row * FF + col0) = w;
	v_exp_f32_e32 v98, v98
	s_nop 0
	v_add_f32_e32 v98, 1.0, v98
	v_rcp_f32_e32 v98, v98
	s_nop 0
	v_mul_f32_e32 v97, v97, v98
	v_mul_f32_e32 v99, v96, v97
	v_cvt_pk_bf16_f32 v96, v116, v108
	v_cvt_pk_bf16_f32 v97, v106, v107
	v_cvt_pk_bf16_f32 v98, v104, v100
	v_cvt_pk_bf16_f32 v99, v101, v99
	v_mad_i64_i32 v[100:101], s[16:17], v162, s3, v[112:113]
	v_lshl_add_u64 v[100:101], v[100:101], 0, v[114:115]
	global_store_dwordx4 v[100:101], v[96:99], off
	s_nop 1
	v_mov_b32_e32 v96, v88
	v_mov_b32_e32 v97, v92
	v_pk_mul_f32 v[96:97], v[96:97], v[244:245] op_sel_hi:[1,0]
	v_mov_b32_e32 v92, v89
	v_mul_f32_e32 v88, 0xbfb8aa3b, v97
	v_exp_f32_e32 v88, v88
	s_nop 0
	v_add_f32_e32 v88, 1.0, v88
	v_rcp_f32_e32 v88, v88
	s_nop 0
	v_mul_f32_e32 v88, v97, v88
	v_mul_f32_e32 v96, v96, v88
	v_pk_mul_f32 v[88:89], v[92:93], v[244:245] op_sel_hi:[1,0]
	s_nop 0
	v_mul_f32_e32 v92, 0xbfb8aa3b, v89
	v_exp_f32_e32 v92, v92
	s_nop 0
	v_add_f32_e32 v92, 1.0, v92
	v_rcp_f32_e32 v92, v92
	s_nop 0
	v_mul_f32_e32 v89, v89, v92
	v_mul_f32_e32 v92, v88, v89
	v_mov_b32_e32 v88, v90
	v_mov_b32_e32 v89, v94
	v_pk_mul_f32 v[88:89], v[88:89], v[244:245] op_sel_hi:[1,0]
	v_mov_b32_e32 v94, v91
	v_mul_f32_e32 v90, 0xbfb8aa3b, v89
	v_exp_f32_e32 v90, v90
	s_nop 0
	v_add_f32_e32 v90, 1.0, v90
	v_rcp_f32_e32 v90, v90
	s_nop 0
	v_mul_f32_e32 v89, v89, v90
	v_mul_f32_e32 v90, v88, v89
	v_pk_mul_f32 v[88:89], v[94:95], v[244:245] op_sel_hi:[1,0]
	s_nop 0
	v_mul_f32_e32 v91, 0xbfb8aa3b, v89
	v_exp_f32_e32 v91, v91
	s_nop 0
	v_add_f32_e32 v91, 1.0, v91
	v_rcp_f32_e32 v91, v91
	s_nop 0
	v_mul_f32_e32 v89, v89, v91
	v_mul_f32_e32 v91, v88, v89
	v_mov_b32_e32 v88, v80
	v_mov_b32_e32 v89, v84
	v_pk_mul_f32 v[88:89], v[88:89], v[244:245] op_sel_hi:[1,0]
	v_mov_b32_e32 v84, v81
	v_mul_f32_e32 v80, 0xbfb8aa3b, v89
	v_exp_f32_e32 v80, v80
	s_nop 0
	v_add_f32_e32 v80, 1.0, v80
	v_rcp_f32_e32 v80, v80
	s_nop 0
	v_mul_f32_e32 v80, v89, v80
	v_mul_f32_e32 v88, v88, v80
	v_pk_mul_f32 v[80:81], v[84:85], v[244:245] op_sel_hi:[1,0]
	s_nop 0
	v_mul_f32_e32 v84, 0xbfb8aa3b, v81
	v_exp_f32_e32 v84, v84
	s_nop 0
	v_add_f32_e32 v84, 1.0, v84
	v_rcp_f32_e32 v84, v84
	s_nop 0
	v_mul_f32_e32 v81, v81, v84
	v_mul_f32_e32 v84, v80, v81
	v_mov_b32_e32 v80, v82
	v_mov_b32_e32 v81, v86
	v_pk_mul_f32 v[80:81], v[80:81], v[244:245] op_sel_hi:[1,0]
	v_mov_b32_e32 v86, v83
	v_mul_f32_e32 v82, 0xbfb8aa3b, v81
	v_exp_f32_e32 v82, v82
	s_nop 0
	v_add_f32_e32 v82, 1.0, v82
	v_rcp_f32_e32 v82, v82
	s_nop 0
	v_mul_f32_e32 v81, v81, v82
	v_mul_f32_e32 v85, v80, v81
	v_pk_mul_f32 v[80:81], v[86:87], v[244:245] op_sel_hi:[1,0]
	s_nop 0
	v_mul_f32_e32 v82, 0xbfb8aa3b, v81
	v_exp_f32_e32 v82, v82
	s_nop 0
	v_add_f32_e32 v82, 1.0, v82
	v_rcp_f32_e32 v82, v82
	s_nop 0
	v_mul_f32_e32 v81, v81, v82
	v_mul_f32_e32 v83, v80, v81
	v_cvt_pk_bf16_f32 v80, v96, v92
	v_cvt_pk_bf16_f32 v81, v90, v91
	v_cvt_pk_bf16_f32 v82, v88, v84
	v_cvt_pk_bf16_f32 v83, v85, v83
	v_mad_i64_i32 v[84:85], s[16:17], v158, s3, v[112:113]
	v_lshl_add_u64 v[84:85], v[84:85], 0, v[114:115]
	global_store_dwordx4 v[84:85], v[80:83], off
	s_nop 1
	v_mov_b32_e32 v80, v72
	v_mov_b32_e32 v81, v76
	v_pk_mul_f32 v[80:81], v[80:81], v[186:187] op_sel_hi:[1,0]
	v_mov_b32_e32 v76, v73
	v_mul_f32_e32 v72, 0xbfb8aa3b, v81
	v_exp_f32_e32 v72, v72
	s_nop 0
	v_add_f32_e32 v72, 1.0, v72
	v_rcp_f32_e32 v72, v72
	s_nop 0
	v_mul_f32_e32 v72, v81, v72
	v_mul_f32_e32 v80, v80, v72
	v_pk_mul_f32 v[72:73], v[76:77], v[186:187] op_sel_hi:[1,0]
	s_nop 0
	v_mul_f32_e32 v76, 0xbfb8aa3b, v73
	v_exp_f32_e32 v76, v76
	s_nop 0
	v_add_f32_e32 v76, 1.0, v76
	v_rcp_f32_e32 v76, v76
	s_nop 0
	v_mul_f32_e32 v73, v73, v76
	v_mul_f32_e32 v76, v72, v73
	v_mov_b32_e32 v72, v74
	v_mov_b32_e32 v73, v78
	v_pk_mul_f32 v[72:73], v[72:73], v[186:187] op_sel_hi:[1,0]
	v_mov_b32_e32 v78, v75
	v_mul_f32_e32 v74, 0xbfb8aa3b, v73
	v_exp_f32_e32 v74, v74
	s_nop 0
	v_add_f32_e32 v74, 1.0, v74
	v_rcp_f32_e32 v74, v74
	s_nop 0
	v_mul_f32_e32 v73, v73, v74
	v_mul_f32_e32 v74, v72, v73
	v_pk_mul_f32 v[72:73], v[78:79], v[186:187] op_sel_hi:[1,0]
	s_nop 0
	v_mul_f32_e32 v75, 0xbfb8aa3b, v73
	v_exp_f32_e32 v75, v75
	s_nop 0
	v_add_f32_e32 v75, 1.0, v75
	v_rcp_f32_e32 v75, v75
	s_nop 0
	v_mul_f32_e32 v73, v73, v75
	v_mul_f32_e32 v75, v72, v73
	v_mov_b32_e32 v72, v64
	v_mov_b32_e32 v73, v68
	v_pk_mul_f32 v[72:73], v[72:73], v[186:187] op_sel_hi:[1,0]
	v_mov_b32_e32 v68, v65
	v_mul_f32_e32 v64, 0xbfb8aa3b, v73
	v_exp_f32_e32 v64, v64
	s_nop 0
	v_add_f32_e32 v64, 1.0, v64
	v_rcp_f32_e32 v64, v64
	s_nop 0
	v_mul_f32_e32 v64, v73, v64
	v_mul_f32_e32 v72, v72, v64
	v_pk_mul_f32 v[64:65], v[68:69], v[186:187] op_sel_hi:[1,0]
	s_nop 0
	v_mul_f32_e32 v68, 0xbfb8aa3b, v65
	v_exp_f32_e32 v68, v68
	s_nop 0
	v_add_f32_e32 v68, 1.0, v68
	v_rcp_f32_e32 v68, v68
	s_nop 0
	v_mul_f32_e32 v65, v65, v68
	v_mul_f32_e32 v68, v64, v65
	v_mov_b32_e32 v64, v66
	v_mov_b32_e32 v65, v70
	v_pk_mul_f32 v[64:65], v[64:65], v[186:187] op_sel_hi:[1,0]
	v_mov_b32_e32 v70, v67
	v_mul_f32_e32 v66, 0xbfb8aa3b, v65
	v_exp_f32_e32 v66, v66
	s_nop 0
	v_add_f32_e32 v66, 1.0, v66
	v_rcp_f32_e32 v66, v66
	s_nop 0
	v_mul_f32_e32 v65, v65, v66
	v_mul_f32_e32 v69, v64, v65
	v_pk_mul_f32 v[64:65], v[70:71], v[186:187] op_sel_hi:[1,0]
	s_nop 0
	v_mul_f32_e32 v66, 0xbfb8aa3b, v65
	v_exp_f32_e32 v66, v66
	s_nop 0
	v_add_f32_e32 v66, 1.0, v66
	v_rcp_f32_e32 v66, v66
	s_nop 0
	v_mul_f32_e32 v65, v65, v66
	v_mul_f32_e32 v67, v64, v65
	v_cvt_pk_bf16_f32 v64, v80, v76
	v_cvt_pk_bf16_f32 v65, v74, v75
	v_cvt_pk_bf16_f32 v66, v72, v68
	v_cvt_pk_bf16_f32 v67, v69, v67
	v_mad_i64_i32 v[68:69], s[16:17], v154, s3, v[112:113]
	v_lshl_add_u64 v[68:69], v[68:69], 0, v[114:115]
; __device__ __forceinline__ unsigned cvt_pk_bf16(float lo, float hi) { unsigned r; asm volatile("v_cvt_pk_bf16_f32 %0, %1, %2" : "=v"(r) : "v"(lo), "v"(hi)); return r; }
; __device__ __forceinline__ float sigmoidf_(float x) { return __builtin_amdgcn_rcpf(1.0f + __expf(-x)); }
;     __device__ __forceinline__ void operator()(const f32x4 (&acc)[2][2][4][2], const Unit& u, int wr, int wc, int fr, int fq) const {
;     ...
;         for (int ai = 0; ai < 2; ++ai)
; #pragma unroll
;             for (int m = 0; m < 4; ++m) {
;                 const int row = row0 + ai * 128 + m * 16; const float s = sv[ai][m];
;                 float o[8];
; #pragma unroll
;                 for (int n = 0; n < 2; ++n)
; #pragma unroll
;                     for (int j = 0; j < 4; ++j) { const float g = acc[ai][0][m][n][j] * s, up = acc[ai][1][m][n][j] * s; o[n * 4 + j] = g * sigmoidf_(g) * up; }
;                 u32x4 w; w.x = cvt_pk_bf16(o[0], o[1]); w.y = cvt_pk_bf16(o[2], o[3]); w.z = cvt_pk_bf16(o[4], o[5]); w.w = cvt_pk_bf16(o[6], o[7]);
;                 *(u32x4*)(ACT + (size_t)row * FF + col0) = w;
	global_store_dwordx4 v[68:69], v[64:67], off
	s_nop 1
	v_mov_b32_e32 v64, v56
	v_mov_b32_e32 v65, v60
	v_pk_mul_f32 v[64:65], v[64:65], v[152:153] op_sel_hi:[1,0]
	v_mov_b32_e32 v60, v57
	v_mul_f32_e32 v56, 0xbfb8aa3b, v65
	v_exp_f32_e32 v56, v56
	s_nop 0
	v_add_f32_e32 v56, 1.0, v56
	v_rcp_f32_e32 v56, v56
	s_nop 0
	v_mul_f32_e32 v56, v65, v56
	v_mul_f32_e32 v64, v64, v56
	v_pk_mul_f32 v[56:57], v[60:61], v[152:153] op_sel_hi:[1,0]
	s_nop 0
	v_mul_f32_e32 v60, 0xbfb8aa3b, v57
	v_exp_f32_e32 v60, v60
	s_nop 0
	v_add_f32_e32 v60, 1.0, v60
	v_rcp_f32_e32 v60, v60
	s_nop 0
	v_mul_f32_e32 v57, v57, v60
	v_mul_f32_e32 v60, v56, v57
	v_mov_b32_e32 v56, v58
	v_mov_b32_e32 v57, v62
	v_pk_mul_f32 v[56:57], v[56:57], v[152:153] op_sel_hi:[1,0]
	v_mov_b32_e32 v62, v59
	v_mul_f32_e32 v58, 0xbfb8aa3b, v57
	v_exp_f32_e32 v58, v58
	s_nop 0
	v_add_f32_e32 v58, 1.0, v58
	v_rcp_f32_e32 v58, v58
	s_nop 0
	v_mul_f32_e32 v57, v57, v58
	v_mul_f32_e32 v58, v56, v57
	v_pk_mul_f32 v[56:57], v[62:63], v[152:153] op_sel_hi:[1,0]
	s_nop 0
	v_mul_f32_e32 v59, 0xbfb8aa3b, v57
	v_exp_f32_e32 v59, v59
	s_nop 0
	v_add_f32_e32 v59, 1.0, v59
	v_rcp_f32_e32 v59, v59
	s_nop 0
	v_mul_f32_e32 v57, v57, v59
	v_mul_f32_e32 v59, v56, v57
	v_mov_b32_e32 v56, v48
	v_mov_b32_e32 v57, v52
	v_pk_mul_f32 v[56:57], v[56:57], v[152:153] op_sel_hi:[1,0]
	v_mov_b32_e32 v52, v49
	v_mul_f32_e32 v48, 0xbfb8aa3b, v57
	v_exp_f32_e32 v48, v48
	s_nop 0
	v_add_f32_e32 v48, 1.0, v48
	v_rcp_f32_e32 v48, v48
	s_nop 0
	v_mul_f32_e32 v48, v57, v48
	v_mul_f32_e32 v56, v56, v48
	v_pk_mul_f32 v[48:49], v[52:53], v[152:153] op_sel_hi:[1,0]
	s_nop 0
	v_mul_f32_e32 v52, 0xbfb8aa3b, v49
	v_exp_f32_e32 v52, v52
	s_nop 0
	v_add_f32_e32 v52, 1.0, v52
	v_rcp_f32_e32 v52, v52
	s_nop 0
	v_mul_f32_e32 v49, v49, v52
	v_mul_f32_e32 v52, v48, v49
	v_mov_b32_e32 v48, v50
	v_mov_b32_e32 v49, v54
	v_pk_mul_f32 v[48:49], v[48:49], v[152:153] op_sel_hi:[1,0]
	v_mov_b32_e32 v54, v51
	v_mul_f32_e32 v50, 0xbfb8aa3b, v49
	v_exp_f32_e32 v50, v50
	s_nop 0
	v_add_f32_e32 v50, 1.0, v50
	v_rcp_f32_e32 v50, v50
	s_nop 0
	v_mul_f32_e32 v49, v49, v50
	v_mul_f32_e32 v53, v48, v49
	v_pk_mul_f32 v[48:49], v[54:55], v[152:153] op_sel_hi:[1,0]
	s_nop 0
	v_mul_f32_e32 v50, 0xbfb8aa3b, v49
	v_exp_f32_e32 v50, v50
	s_nop 0
	v_add_f32_e32 v50, 1.0, v50
	v_rcp_f32_e32 v50, v50
	s_nop 0
	v_mul_f32_e32 v49, v49, v50
	v_mul_f32_e32 v51, v48, v49
	v_cvt_pk_bf16_f32 v48, v64, v60
	v_cvt_pk_bf16_f32 v49, v58, v59
	v_cvt_pk_bf16_f32 v50, v56, v52
	v_cvt_pk_bf16_f32 v51, v53, v51
	v_mad_i64_i32 v[52:53], s[16:17], v161, s3, v[112:113]
	v_lshl_add_u64 v[52:53], v[52:53], 0, v[114:115]
	global_store_dwordx4 v[52:53], v[48:51], off
	s_nop 1
	v_mov_b32_e32 v48, v40
	v_mov_b32_e32 v49, v44
	v_pk_mul_f32 v[48:49], v[48:49], v[150:151] op_sel_hi:[1,0]
	v_mov_b32_e32 v44, v41
	v_mul_f32_e32 v40, 0xbfb8aa3b, v49
	v_exp_f32_e32 v40, v40
	s_nop 0
	v_add_f32_e32 v40, 1.0, v40
	v_rcp_f32_e32 v40, v40
	s_nop 0
	v_mul_f32_e32 v40, v49, v40
	v_mul_f32_e32 v48, v48, v40
	v_pk_mul_f32 v[40:41], v[44:45], v[150:151] op_sel_hi:[1,0]
	s_nop 0
	v_mul_f32_e32 v44, 0xbfb8aa3b, v41
	v_exp_f32_e32 v44, v44
	s_nop 0
	v_add_f32_e32 v44, 1.0, v44
	v_rcp_f32_e32 v44, v44
	s_nop 0
	v_mul_f32_e32 v41, v41, v44
	v_mul_f32_e32 v44, v40, v41
	v_mov_b32_e32 v40, v42
	v_mov_b32_e32 v41, v46
	v_pk_mul_f32 v[40:41], v[40:41], v[150:151] op_sel_hi:[1,0]
	v_mov_b32_e32 v46, v43
	v_mul_f32_e32 v42, 0xbfb8aa3b, v41
	v_exp_f32_e32 v42, v42
	s_nop 0
	v_add_f32_e32 v42, 1.0, v42
	v_rcp_f32_e32 v42, v42
	s_nop 0
	v_mul_f32_e32 v41, v41, v42
	v_mul_f32_e32 v42, v40, v41
	v_pk_mul_f32 v[40:41], v[46:47], v[150:151] op_sel_hi:[1,0]
	s_nop 0
	v_mul_f32_e32 v43, 0xbfb8aa3b, v41
	v_exp_f32_e32 v43, v43
	s_nop 0
	v_add_f32_e32 v43, 1.0, v43
	v_rcp_f32_e32 v43, v43
	s_nop 0
	v_mul_f32_e32 v41, v41, v43
	v_mul_f32_e32 v43, v40, v41
	v_mov_b32_e32 v40, v32
	v_mov_b32_e32 v41, v36
	v_pk_mul_f32 v[40:41], v[40:41], v[150:151] op_sel_hi:[1,0]
	v_mov_b32_e32 v36, v33
	v_mul_f32_e32 v32, 0xbfb8aa3b, v41
	v_exp_f32_e32 v32, v32
	s_nop 0
	v_add_f32_e32 v32, 1.0, v32
	v_rcp_f32_e32 v32, v32
	s_nop 0
	v_mul_f32_e32 v32, v41, v32
	v_mul_f32_e32 v40, v40, v32
	v_pk_mul_f32 v[32:33], v[36:37], v[150:151] op_sel_hi:[1,0]
	s_nop 0
	v_mul_f32_e32 v36, 0xbfb8aa3b, v33
	v_exp_f32_e32 v36, v36
	s_nop 0
	v_add_f32_e32 v36, 1.0, v36
	v_rcp_f32_e32 v36, v36
	s_nop 0
	v_mul_f32_e32 v33, v33, v36
	v_mul_f32_e32 v36, v32, v33
	v_mov_b32_e32 v32, v34
	v_mov_b32_e32 v33, v38
	v_pk_mul_f32 v[32:33], v[32:33], v[150:151] op_sel_hi:[1,0]
	v_mov_b32_e32 v38, v35
	v_mul_f32_e32 v34, 0xbfb8aa3b, v33
	v_exp_f32_e32 v34, v34
	s_nop 0
	v_add_f32_e32 v34, 1.0, v34
	v_rcp_f32_e32 v34, v34
	s_nop 0
	v_mul_f32_e32 v33, v33, v34
	v_mul_f32_e32 v37, v32, v33
	v_pk_mul_f32 v[32:33], v[38:39], v[150:151] op_sel_hi:[1,0]
	s_nop 0
	v_mul_f32_e32 v34, 0xbfb8aa3b, v33
	v_exp_f32_e32 v34, v34
	s_nop 0
	v_add_f32_e32 v34, 1.0, v34
	v_rcp_f32_e32 v34, v34
	s_nop 0
	v_mul_f32_e32 v33, v33, v34
	v_mul_f32_e32 v35, v32, v33
	v_cvt_pk_bf16_f32 v32, v48, v44
	v_cvt_pk_bf16_f32 v33, v42, v43
	v_cvt_pk_bf16_f32 v34, v40, v36
	v_cvt_pk_bf16_f32 v35, v37, v35
	v_mad_i64_i32 v[36:37], s[16:17], v159, s3, v[112:113]
	v_lshl_add_u64 v[36:37], v[36:37], 0, v[114:115]
; __device__ __forceinline__ unsigned cvt_pk_bf16(float lo, float hi) { unsigned r; asm volatile("v_cvt_pk_bf16_f32 %0, %1, %2" : "=v"(r) : "v"(lo), "v"(hi)); return r; }
; #define PG8_BAR __builtin_amdgcn_s_barrier()
; __device__ __forceinline__ float sigmoidf_(float x) { return __builtin_amdgcn_rcpf(1.0f + __expf(-x)); }
; template <class Epi, class Sched, bool ALIGN_EPI = false, bool SP2 = false>
; __device__ __forceinline__ void gemm_phase(PG8_LAS unsigned char* lds, const Gemm g, const Sched& S, const Epi& E) {
;     ...
;         if constexpr (!Epi::AFTER_DRAIN) { E(acc, cur, wr, wc, fr, fq); S.done(cur); }
;         if (!has_next) break;
; #pragma unroll
;         for (int a = 0; a < 2; ++a)
; #pragma unroll
;             for (int b = 0; b < 2; ++b)
; #pragma unroll
;                 for (int m = 0; m < 4; ++m)
; #pragma unroll
;                     for (int n = 0; n < 2; ++n) acc[a][b][m][n] = (f32x4){0.f, 0.f, 0.f, 0.f};
;         cur = nxt; cA = nA; cB = nB; ++ui;
;         if constexpr (ALIGN_EPI) { if (wr == 1) PG8_BAR; }
;     __device__ __forceinline__ void operator()(const f32x4 (&acc)[2][2][4][2], const Unit& u, int wr, int wc, int fr, int fq) const {
;     ...
;         for (int ai = 0; ai < 2; ++ai)
; #pragma unroll
;             for (int m = 0; m < 4; ++m) {
;                 const int row = row0 + ai * 128 + m * 16; const float s = sv[ai][m];
;                 float o[8];
; #pragma unroll
;                 for (int n = 0; n < 2; ++n)
; #pragma unroll
;                     for (int j = 0; j < 4; ++j) { const float g = acc[ai][0][m][n][j] * s, up = acc[ai][1][m][n][j] * s; o[n * 4 + j] = g * sigmoidf_(g) * up; }
;                 u32x4 w; w.x = cvt_pk_bf16(o[0], o[1]); w.y = cvt_pk_bf16(o[2], o[3]); w.z = cvt_pk_bf16(o[4], o[5]); w.w = cvt_pk_bf16(o[6], o[7]);
;                 *(u32x4*)(ACT + (size_t)row * FF + col0) = w;
	global_store_dwordx4 v[36:37], v[32:35], off
	s_nop 1
	v_mov_b32_e32 v32, v24
	v_mov_b32_e32 v33, v28
	v_pk_mul_f32 v[32:33], v[32:33], v[148:149] op_sel_hi:[1,0]
	v_mov_b32_e32 v28, v25
	v_mul_f32_e32 v24, 0xbfb8aa3b, v33
	v_exp_f32_e32 v24, v24
	s_nop 0
	v_add_f32_e32 v24, 1.0, v24
	v_rcp_f32_e32 v24, v24
	s_nop 0
	v_mul_f32_e32 v24, v33, v24
	v_mul_f32_e32 v32, v32, v24
	v_pk_mul_f32 v[24:25], v[28:29], v[148:149] op_sel_hi:[1,0]
	s_nop 0
	v_mul_f32_e32 v28, 0xbfb8aa3b, v25
	v_exp_f32_e32 v28, v28
	s_nop 0
	v_add_f32_e32 v28, 1.0, v28
	v_rcp_f32_e32 v28, v28
	s_nop 0
	v_mul_f32_e32 v25, v25, v28
	v_mul_f32_e32 v28, v24, v25
	v_mov_b32_e32 v24, v26
	v_mov_b32_e32 v25, v30
	v_pk_mul_f32 v[24:25], v[24:25], v[148:149] op_sel_hi:[1,0]
	v_mov_b32_e32 v30, v27
	v_mul_f32_e32 v26, 0xbfb8aa3b, v25
	v_exp_f32_e32 v26, v26
	s_nop 0
	v_add_f32_e32 v26, 1.0, v26
	v_rcp_f32_e32 v26, v26
	s_nop 0
	v_mul_f32_e32 v25, v25, v26
	v_mul_f32_e32 v26, v24, v25
	v_pk_mul_f32 v[24:25], v[30:31], v[148:149] op_sel_hi:[1,0]
	s_nop 0
	v_mul_f32_e32 v27, 0xbfb8aa3b, v25
	v_exp_f32_e32 v27, v27
	s_nop 0
	v_add_f32_e32 v27, 1.0, v27
	v_rcp_f32_e32 v27, v27
	s_nop 0
	v_mul_f32_e32 v25, v25, v27
	v_mul_f32_e32 v27, v24, v25
	v_mov_b32_e32 v24, v16
	v_mov_b32_e32 v25, v20
	v_pk_mul_f32 v[24:25], v[24:25], v[148:149] op_sel_hi:[1,0]
	v_mov_b32_e32 v20, v17
	v_mul_f32_e32 v16, 0xbfb8aa3b, v25
	v_exp_f32_e32 v16, v16
	s_nop 0
	v_add_f32_e32 v16, 1.0, v16
	v_rcp_f32_e32 v16, v16
	s_nop 0
	v_mul_f32_e32 v16, v25, v16
	v_mul_f32_e32 v24, v24, v16
	v_pk_mul_f32 v[16:17], v[20:21], v[148:149] op_sel_hi:[1,0]
	s_nop 0
	v_mul_f32_e32 v20, 0xbfb8aa3b, v17
	v_exp_f32_e32 v20, v20
	s_nop 0
	v_add_f32_e32 v20, 1.0, v20
	v_rcp_f32_e32 v20, v20
	s_nop 0
	v_mul_f32_e32 v17, v17, v20
	v_mul_f32_e32 v20, v16, v17
	v_mov_b32_e32 v16, v18
	v_mov_b32_e32 v17, v22
	v_pk_mul_f32 v[16:17], v[16:17], v[148:149] op_sel_hi:[1,0]
	v_mov_b32_e32 v22, v19
	v_mul_f32_e32 v18, 0xbfb8aa3b, v17
	v_exp_f32_e32 v18, v18
	s_nop 0
	v_add_f32_e32 v18, 1.0, v18
	v_rcp_f32_e32 v18, v18
	s_nop 0
	v_mul_f32_e32 v17, v17, v18
	v_mul_f32_e32 v21, v16, v17
	v_pk_mul_f32 v[16:17], v[22:23], v[148:149] op_sel_hi:[1,0]
	s_nop 0
	v_mul_f32_e32 v18, 0xbfb8aa3b, v17
	v_exp_f32_e32 v18, v18
	s_nop 0
	v_add_f32_e32 v18, 1.0, v18
	v_rcp_f32_e32 v18, v18
	s_nop 0
	v_mul_f32_e32 v17, v17, v18
	v_mul_f32_e32 v19, v16, v17
	v_cvt_pk_bf16_f32 v16, v32, v28
	v_cvt_pk_bf16_f32 v17, v26, v27
	v_cvt_pk_bf16_f32 v18, v24, v20
	v_cvt_pk_bf16_f32 v19, v21, v19
	v_mad_i64_i32 v[20:21], s[16:17], v157, s3, v[112:113]
	v_lshl_add_u64 v[20:21], v[20:21], 0, v[114:115]
	global_store_dwordx4 v[20:21], v[16:19], off
	s_nop 1
	v_mov_b32_e32 v16, v8
	v_mov_b32_e32 v17, v12
	v_pk_mul_f32 v[16:17], v[16:17], v[188:189] op_sel_hi:[1,0]
	v_mov_b32_e32 v12, v9
	v_mul_f32_e32 v8, 0xbfb8aa3b, v17
	v_exp_f32_e32 v8, v8
	s_nop 0
	v_add_f32_e32 v8, 1.0, v8
	v_rcp_f32_e32 v8, v8
	s_nop 0
	v_mul_f32_e32 v8, v17, v8
	v_mul_f32_e32 v16, v16, v8
	v_pk_mul_f32 v[8:9], v[12:13], v[188:189] op_sel_hi:[1,0]
	s_nop 0
	v_mul_f32_e32 v12, 0xbfb8aa3b, v9
	v_exp_f32_e32 v12, v12
	s_nop 0
	v_add_f32_e32 v12, 1.0, v12
	v_rcp_f32_e32 v12, v12
	s_nop 0
	v_mul_f32_e32 v9, v9, v12
	v_mul_f32_e32 v12, v8, v9
	v_mov_b32_e32 v8, v10
	v_mov_b32_e32 v9, v14
	v_pk_mul_f32 v[8:9], v[8:9], v[188:189] op_sel_hi:[1,0]
	v_mov_b32_e32 v14, v11
	v_mul_f32_e32 v10, 0xbfb8aa3b, v9
	v_exp_f32_e32 v10, v10
	s_nop 0
	v_add_f32_e32 v10, 1.0, v10
	v_rcp_f32_e32 v10, v10
	s_nop 0
	v_mul_f32_e32 v9, v9, v10
	v_mul_f32_e32 v10, v8, v9
	v_pk_mul_f32 v[8:9], v[14:15], v[188:189] op_sel_hi:[1,0]
	s_nop 0
	v_mul_f32_e32 v11, 0xbfb8aa3b, v9
	v_exp_f32_e32 v11, v11
	s_nop 0
	v_add_f32_e32 v11, 1.0, v11
	v_rcp_f32_e32 v11, v11
	s_nop 0
	v_mul_f32_e32 v9, v9, v11
	v_mul_f32_e32 v11, v8, v9
	v_mov_b32_e32 v8, v0
	v_mov_b32_e32 v9, v4
	v_pk_mul_f32 v[8:9], v[8:9], v[188:189] op_sel_hi:[1,0]
	v_mov_b32_e32 v4, v1
	v_mul_f32_e32 v0, 0xbfb8aa3b, v9
	v_exp_f32_e32 v0, v0
	s_nop 0
	v_add_f32_e32 v0, 1.0, v0
	v_rcp_f32_e32 v0, v0
	s_nop 0
	v_mul_f32_e32 v0, v9, v0
	v_mul_f32_e32 v8, v8, v0
	v_pk_mul_f32 v[0:1], v[4:5], v[188:189] op_sel_hi:[1,0]
	s_nop 0
	v_mul_f32_e32 v4, 0xbfb8aa3b, v1
	v_exp_f32_e32 v4, v4
	s_nop 0
	v_add_f32_e32 v4, 1.0, v4
	v_rcp_f32_e32 v4, v4
	s_nop 0
	v_mul_f32_e32 v1, v1, v4
	v_mul_f32_e32 v4, v0, v1
	v_mov_b32_e32 v0, v2
	v_mov_b32_e32 v1, v6
	v_pk_mul_f32 v[0:1], v[0:1], v[188:189] op_sel_hi:[1,0]
	v_mov_b32_e32 v6, v3
	v_mul_f32_e32 v2, 0xbfb8aa3b, v1
	v_exp_f32_e32 v2, v2
	s_nop 0
	v_add_f32_e32 v2, 1.0, v2
	v_rcp_f32_e32 v2, v2
	s_nop 0
	v_mul_f32_e32 v1, v1, v2
	v_mul_f32_e32 v5, v0, v1
	v_pk_mul_f32 v[0:1], v[6:7], v[188:189] op_sel_hi:[1,0]
	s_nop 0
	v_mul_f32_e32 v2, 0xbfb8aa3b, v1
	v_exp_f32_e32 v2, v2
	s_nop 0
	v_add_f32_e32 v2, 1.0, v2
	v_rcp_f32_e32 v2, v2
	s_nop 0
	v_mul_f32_e32 v1, v1, v2
	v_mul_f32_e32 v3, v0, v1
	v_cvt_pk_bf16_f32 v0, v16, v12
	v_cvt_pk_bf16_f32 v1, v10, v11
	v_cvt_pk_bf16_f32 v2, v8, v4
	v_cvt_pk_bf16_f32 v3, v5, v3
	v_mad_i64_i32 v[4:5], s[16:17], v155, s3, v[112:113]
	v_lshl_add_u64 v[4:5], v[4:5], 0, v[114:115]
	s_mov_b64 s[16:17], -1
	global_store_dwordx4 v[4:5], v[0:3], off
	s_cbranch_vccnz .LBB0_721
	s_andn2_b64 vcc, exec, s[0:1]
	s_cbranch_vccnz .LBB0_720
	s_barrier
	s_branch .LBB0_720
